# conv LayerNorm butterfly: 48 ds_bpermute round trips per unit replaced by DPP moves and permlane16/32 swaps (bit-identical sums)
# baseline (speedup 1.0000x reference)
; __device__ __forceinline__ float bf_lo(unsigned w) { return __uint_as_float(w << 16); }
; __device__ __forceinline__ float bf_hi(unsigned w) { return __uint_as_float(w & 0xffff0000u); }
; __device__ __forceinline__ void conv_phase(const Frame& F, const bf16* CG, bf16* CAT, const float* dw_w, const float* dw_b, const float* ln_g, const float* ln_b) {
;     ...
;             unsigned xin[46];
; #pragma unroll
;             for (int r = 0; r < 46; ++r) xin[r] = it[(th * 16 + r) * 256 + cp];
; #pragma unroll
;             for (int r = 0; r < 46; ++r) {
;                 const unsigned v = xin[r]; const f32x2 x = (f32x2){bf_lo(v), bf_hi(v)};
; #pragma unroll
;                 for (int tt = 0; tt < 16; ++tt) { const int j = r - tt; if (j >= 0 && j < KC) a[tt] += w[j] * x; }
;             }
.LBB0_283:
	ds_read2st64_b32 v[78:79], v190 offset1:4
	ds_read2st64_b32 v[80:81], v190 offset0:8 offset1:12
	ds_read2st64_b32 v[82:83], v190 offset0:16 offset1:20
	ds_read2st64_b32 v[152:153], v190 offset0:24 offset1:28
	ds_read2st64_b32 v[154:155], v190 offset0:32 offset1:36
	ds_read2st64_b32 v[156:157], v190 offset0:40 offset1:44
	ds_read2st64_b32 v[158:159], v190 offset0:48 offset1:52
	ds_read2st64_b32 v[160:161], v190 offset0:56 offset1:60
	ds_read2st64_b32 v[162:163], v190 offset0:64 offset1:68
	ds_read2st64_b32 v[76:77], v190 offset0:72 offset1:76
	ds_read2st64_b32 v[74:75], v190 offset0:80 offset1:84
	ds_read2st64_b32 v[72:73], v190 offset0:88 offset1:92
	ds_read2st64_b32 v[70:71], v190 offset0:96 offset1:100
	ds_read2st64_b32 v[68:69], v190 offset0:104 offset1:108
	ds_read2st64_b32 v[66:67], v190 offset0:112 offset1:116
	ds_read2st64_b32 v[64:65], v190 offset0:120 offset1:124
	ds_read2st64_b32 v[62:63], v190 offset0:128 offset1:132
	ds_read2st64_b32 v[60:61], v190 offset0:136 offset1:140
	ds_read2st64_b32 v[58:59], v190 offset0:144 offset1:148
	ds_read2st64_b32 v[56:57], v190 offset0:152 offset1:156
	ds_read2st64_b32 v[54:55], v190 offset0:160 offset1:164
	ds_read2st64_b32 v[52:53], v190 offset0:168 offset1:172
	ds_read2st64_b32 v[2:3], v190 offset0:176 offset1:180
	s_waitcnt lgkmcnt(14)
	v_lshlrev_b32_e32 v164, 16, v78
	v_and_b32_e32 v165, 0xffff0000, v78
	v_pk_fma_f32 v[164:165], v[142:143], v[164:165], v[146:147]
	v_lshlrev_b32_e32 v78, 16, v79
	v_and_b32_e32 v79, 0xffff0000, v79
	v_pk_fma_f32 v[164:165], v[144:145], v[78:79], v[164:165]
	v_pk_fma_f32 v[78:79], v[142:143], v[78:79], v[146:147]
	v_lshlrev_b32_e32 v166, 16, v80
	v_and_b32_e32 v167, 0xffff0000, v80
	v_pk_fma_f32 v[164:165], v[92:93], v[166:167], v[164:165]
	v_pk_fma_f32 v[78:79], v[144:145], v[166:167], v[78:79]
	v_pk_fma_f32 v[166:167], v[142:143], v[166:167], v[146:147]
	v_lshlrev_b32_e32 v80, 16, v81
	v_and_b32_e32 v81, 0xffff0000, v81
	v_pk_fma_f32 v[164:165], v[94:95], v[80:81], v[164:165]
	v_pk_fma_f32 v[78:79], v[92:93], v[80:81], v[78:79]
	v_pk_fma_f32 v[166:167], v[144:145], v[80:81], v[166:167]
	v_pk_fma_f32 v[80:81], v[142:143], v[80:81], v[146:147]
	v_lshlrev_b32_e32 v168, 16, v82
	v_and_b32_e32 v169, 0xffff0000, v82
	v_pk_fma_f32 v[164:165], v[84:85], v[168:169], v[164:165]
	v_pk_fma_f32 v[78:79], v[94:95], v[168:169], v[78:79]
	v_pk_fma_f32 v[166:167], v[92:93], v[168:169], v[166:167]
	v_pk_fma_f32 v[80:81], v[144:145], v[168:169], v[80:81]
	v_pk_fma_f32 v[168:169], v[142:143], v[168:169], v[146:147]
	v_lshlrev_b32_e32 v82, 16, v83
	v_and_b32_e32 v83, 0xffff0000, v83
	v_pk_fma_f32 v[164:165], v[96:97], v[82:83], v[164:165]
	v_pk_fma_f32 v[78:79], v[84:85], v[82:83], v[78:79]
	v_pk_fma_f32 v[166:167], v[94:95], v[82:83], v[166:167]
	v_pk_fma_f32 v[80:81], v[92:93], v[82:83], v[80:81]
	v_pk_fma_f32 v[168:169], v[144:145], v[82:83], v[168:169]
	v_pk_fma_f32 v[82:83], v[142:143], v[82:83], v[146:147]
	v_lshlrev_b32_e32 v170, 16, v152
	v_and_b32_e32 v171, 0xffff0000, v152
	v_pk_fma_f32 v[164:165], v[86:87], v[170:171], v[164:165]
	v_pk_fma_f32 v[78:79], v[96:97], v[170:171], v[78:79]
	v_pk_fma_f32 v[166:167], v[84:85], v[170:171], v[166:167]
	v_pk_fma_f32 v[80:81], v[94:95], v[170:171], v[80:81]
	v_pk_fma_f32 v[168:169], v[92:93], v[170:171], v[168:169]
	v_pk_fma_f32 v[82:83], v[144:145], v[170:171], v[82:83]
	v_pk_fma_f32 v[170:171], v[142:143], v[170:171], v[146:147]
	v_lshlrev_b32_e32 v152, 16, v153
	v_and_b32_e32 v153, 0xffff0000, v153
	v_pk_fma_f32 v[164:165], v[88:89], v[152:153], v[164:165]
	v_pk_fma_f32 v[78:79], v[86:87], v[152:153], v[78:79]
	v_pk_fma_f32 v[166:167], v[96:97], v[152:153], v[166:167]
	v_pk_fma_f32 v[80:81], v[84:85], v[152:153], v[80:81]
	v_pk_fma_f32 v[168:169], v[94:95], v[152:153], v[168:169]
	v_pk_fma_f32 v[82:83], v[92:93], v[152:153], v[82:83]
	v_pk_fma_f32 v[170:171], v[144:145], v[152:153], v[170:171]
	v_pk_fma_f32 v[152:153], v[142:143], v[152:153], v[146:147]
	v_lshlrev_b32_e32 v172, 16, v154
	v_and_b32_e32 v173, 0xffff0000, v154
	v_pk_fma_f32 v[164:165], v[90:91], v[172:173], v[164:165]
	v_pk_fma_f32 v[78:79], v[88:89], v[172:173], v[78:79]
	v_pk_fma_f32 v[166:167], v[86:87], v[172:173], v[166:167]
	v_pk_fma_f32 v[80:81], v[96:97], v[172:173], v[80:81]
	v_pk_fma_f32 v[168:169], v[84:85], v[172:173], v[168:169]
	v_pk_fma_f32 v[82:83], v[94:95], v[172:173], v[82:83]
	v_pk_fma_f32 v[170:171], v[92:93], v[172:173], v[170:171]
	v_pk_fma_f32 v[152:153], v[144:145], v[172:173], v[152:153]
	v_pk_fma_f32 v[172:173], v[142:143], v[172:173], v[146:147]
	v_lshlrev_b32_e32 v154, 16, v155
	v_and_b32_e32 v155, 0xffff0000, v155
	v_pk_fma_f32 v[164:165], v[98:99], v[154:155], v[164:165]
	v_pk_fma_f32 v[78:79], v[90:91], v[154:155], v[78:79]
	v_pk_fma_f32 v[166:167], v[88:89], v[154:155], v[166:167]
	v_pk_fma_f32 v[80:81], v[86:87], v[154:155], v[80:81]
	v_pk_fma_f32 v[168:169], v[96:97], v[154:155], v[168:169]
	v_pk_fma_f32 v[82:83], v[84:85], v[154:155], v[82:83]
	v_pk_fma_f32 v[170:171], v[94:95], v[154:155], v[170:171]
	v_pk_fma_f32 v[152:153], v[92:93], v[154:155], v[152:153]
	v_pk_fma_f32 v[172:173], v[144:145], v[154:155], v[172:173]
	v_pk_fma_f32 v[154:155], v[142:143], v[154:155], v[146:147]
	v_lshlrev_b32_e32 v174, 16, v156
	v_and_b32_e32 v175, 0xffff0000, v156
	v_pk_fma_f32 v[164:165], v[100:101], v[174:175], v[164:165]
	v_pk_fma_f32 v[78:79], v[98:99], v[174:175], v[78:79]
	v_pk_fma_f32 v[166:167], v[90:91], v[174:175], v[166:167]
	v_pk_fma_f32 v[80:81], v[88:89], v[174:175], v[80:81]
	v_pk_fma_f32 v[168:169], v[86:87], v[174:175], v[168:169]
	v_pk_fma_f32 v[82:83], v[96:97], v[174:175], v[82:83]
; __device__ __forceinline__ float bf_lo(unsigned w) { return __uint_as_float(w << 16); }
; __device__ __forceinline__ float bf_hi(unsigned w) { return __uint_as_float(w & 0xffff0000u); }
; __device__ __forceinline__ void conv_phase(const Frame& F, const bf16* CG, bf16* CAT, const float* dw_w, const float* dw_b, const float* ln_g, const float* ln_b) {
;     ...
;             for (int r = 0; r < 46; ++r) {
;                 const unsigned v = xin[r]; const f32x2 x = (f32x2){bf_lo(v), bf_hi(v)};
; #pragma unroll
;                 for (int tt = 0; tt < 16; ++tt) { const int j = r - tt; if (j >= 0 && j < KC) a[tt] += w[j] * x; }
;             }
	v_pk_fma_f32 v[170:171], v[84:85], v[174:175], v[170:171]
	v_pk_fma_f32 v[152:153], v[94:95], v[174:175], v[152:153]
	v_pk_fma_f32 v[172:173], v[92:93], v[174:175], v[172:173]
	v_pk_fma_f32 v[154:155], v[144:145], v[174:175], v[154:155]
	v_pk_fma_f32 v[174:175], v[142:143], v[174:175], v[146:147]
	v_lshlrev_b32_e32 v156, 16, v157
	v_and_b32_e32 v157, 0xffff0000, v157
	v_pk_fma_f32 v[164:165], v[102:103], v[156:157], v[164:165]
	v_pk_fma_f32 v[78:79], v[100:101], v[156:157], v[78:79]
	v_pk_fma_f32 v[166:167], v[98:99], v[156:157], v[166:167]
	v_pk_fma_f32 v[80:81], v[90:91], v[156:157], v[80:81]
	v_pk_fma_f32 v[168:169], v[88:89], v[156:157], v[168:169]
	v_pk_fma_f32 v[82:83], v[86:87], v[156:157], v[82:83]
	v_pk_fma_f32 v[170:171], v[96:97], v[156:157], v[170:171]
	v_pk_fma_f32 v[152:153], v[84:85], v[156:157], v[152:153]
	v_pk_fma_f32 v[172:173], v[94:95], v[156:157], v[172:173]
	v_pk_fma_f32 v[154:155], v[92:93], v[156:157], v[154:155]
	v_pk_fma_f32 v[174:175], v[144:145], v[156:157], v[174:175]
	v_pk_fma_f32 v[156:157], v[142:143], v[156:157], v[146:147]
	v_lshlrev_b32_e32 v176, 16, v158
	v_and_b32_e32 v177, 0xffff0000, v158
	v_pk_fma_f32 v[164:165], v[104:105], v[176:177], v[164:165]
	v_pk_fma_f32 v[78:79], v[102:103], v[176:177], v[78:79]
	v_pk_fma_f32 v[166:167], v[100:101], v[176:177], v[166:167]
	v_pk_fma_f32 v[80:81], v[98:99], v[176:177], v[80:81]
	v_pk_fma_f32 v[168:169], v[90:91], v[176:177], v[168:169]
	v_pk_fma_f32 v[82:83], v[88:89], v[176:177], v[82:83]
	v_pk_fma_f32 v[170:171], v[86:87], v[176:177], v[170:171]
	v_pk_fma_f32 v[152:153], v[96:97], v[176:177], v[152:153]
	v_pk_fma_f32 v[172:173], v[84:85], v[176:177], v[172:173]
	v_pk_fma_f32 v[154:155], v[94:95], v[176:177], v[154:155]
	v_pk_fma_f32 v[174:175], v[92:93], v[176:177], v[174:175]
	v_pk_fma_f32 v[156:157], v[144:145], v[176:177], v[156:157]
	v_pk_fma_f32 v[176:177], v[142:143], v[176:177], v[146:147]
	v_lshlrev_b32_e32 v158, 16, v159
	v_and_b32_e32 v159, 0xffff0000, v159
	v_pk_fma_f32 v[164:165], v[124:125], v[158:159], v[164:165]
	v_pk_fma_f32 v[78:79], v[104:105], v[158:159], v[78:79]
	v_pk_fma_f32 v[166:167], v[102:103], v[158:159], v[166:167]
	v_pk_fma_f32 v[80:81], v[100:101], v[158:159], v[80:81]
	v_pk_fma_f32 v[168:169], v[98:99], v[158:159], v[168:169]
	v_pk_fma_f32 v[82:83], v[90:91], v[158:159], v[82:83]
	v_pk_fma_f32 v[170:171], v[88:89], v[158:159], v[170:171]
	v_pk_fma_f32 v[152:153], v[86:87], v[158:159], v[152:153]
	v_pk_fma_f32 v[172:173], v[96:97], v[158:159], v[172:173]
	v_pk_fma_f32 v[154:155], v[84:85], v[158:159], v[154:155]
	v_pk_fma_f32 v[174:175], v[94:95], v[158:159], v[174:175]
	v_pk_fma_f32 v[156:157], v[92:93], v[158:159], v[156:157]
	v_pk_fma_f32 v[176:177], v[144:145], v[158:159], v[176:177]
	v_pk_fma_f32 v[158:159], v[142:143], v[158:159], v[146:147]
	v_lshlrev_b32_e32 v178, 16, v160
	v_and_b32_e32 v179, 0xffff0000, v160
	v_pk_fma_f32 v[164:165], v[106:107], v[178:179], v[164:165]
	v_pk_fma_f32 v[78:79], v[124:125], v[178:179], v[78:79]
	v_pk_fma_f32 v[166:167], v[104:105], v[178:179], v[166:167]
	v_pk_fma_f32 v[80:81], v[102:103], v[178:179], v[80:81]
	v_pk_fma_f32 v[168:169], v[100:101], v[178:179], v[168:169]
	v_pk_fma_f32 v[82:83], v[98:99], v[178:179], v[82:83]
	v_pk_fma_f32 v[170:171], v[90:91], v[178:179], v[170:171]
	v_pk_fma_f32 v[152:153], v[88:89], v[178:179], v[152:153]
	v_pk_fma_f32 v[172:173], v[86:87], v[178:179], v[172:173]
	v_pk_fma_f32 v[154:155], v[96:97], v[178:179], v[154:155]
	v_pk_fma_f32 v[174:175], v[84:85], v[178:179], v[174:175]
	v_pk_fma_f32 v[156:157], v[94:95], v[178:179], v[156:157]
	v_pk_fma_f32 v[176:177], v[92:93], v[178:179], v[176:177]
	v_pk_fma_f32 v[158:159], v[144:145], v[178:179], v[158:159]
	v_pk_fma_f32 v[178:179], v[142:143], v[178:179], v[146:147]
	v_lshlrev_b32_e32 v160, 16, v161
	v_and_b32_e32 v161, 0xffff0000, v161
	v_pk_fma_f32 v[164:165], v[108:109], v[160:161], v[164:165]
	v_pk_fma_f32 v[78:79], v[106:107], v[160:161], v[78:79]
	v_pk_fma_f32 v[166:167], v[124:125], v[160:161], v[166:167]
	v_pk_fma_f32 v[80:81], v[104:105], v[160:161], v[80:81]
	v_pk_fma_f32 v[168:169], v[102:103], v[160:161], v[168:169]
	v_pk_fma_f32 v[82:83], v[100:101], v[160:161], v[82:83]
	v_pk_fma_f32 v[170:171], v[98:99], v[160:161], v[170:171]
	v_pk_fma_f32 v[152:153], v[90:91], v[160:161], v[152:153]
	v_pk_fma_f32 v[172:173], v[88:89], v[160:161], v[172:173]
	v_pk_fma_f32 v[154:155], v[86:87], v[160:161], v[154:155]
	v_pk_fma_f32 v[174:175], v[96:97], v[160:161], v[174:175]
	v_pk_fma_f32 v[156:157], v[84:85], v[160:161], v[156:157]
	v_pk_fma_f32 v[176:177], v[94:95], v[160:161], v[176:177]
	v_pk_fma_f32 v[158:159], v[92:93], v[160:161], v[158:159]
	v_pk_fma_f32 v[178:179], v[144:145], v[160:161], v[178:179]
	v_pk_fma_f32 v[160:161], v[142:143], v[160:161], v[146:147]
	v_lshlrev_b32_e32 v180, 16, v162
	v_and_b32_e32 v181, 0xffff0000, v162
	v_pk_fma_f32 v[164:165], v[110:111], v[180:181], v[164:165]
	v_pk_fma_f32 v[78:79], v[108:109], v[180:181], v[78:79]
	v_pk_fma_f32 v[166:167], v[106:107], v[180:181], v[166:167]
	v_pk_fma_f32 v[80:81], v[124:125], v[180:181], v[80:81]
	v_pk_fma_f32 v[168:169], v[104:105], v[180:181], v[168:169]
	v_pk_fma_f32 v[82:83], v[102:103], v[180:181], v[82:83]
	v_pk_fma_f32 v[170:171], v[100:101], v[180:181], v[170:171]
	v_pk_fma_f32 v[152:153], v[98:99], v[180:181], v[152:153]
	v_pk_fma_f32 v[172:173], v[90:91], v[180:181], v[172:173]
	v_pk_fma_f32 v[154:155], v[88:89], v[180:181], v[154:155]
	v_pk_fma_f32 v[174:175], v[86:87], v[180:181], v[174:175]
	v_pk_fma_f32 v[156:157], v[96:97], v[180:181], v[156:157]
	v_pk_fma_f32 v[176:177], v[84:85], v[180:181], v[176:177]
	v_pk_fma_f32 v[158:159], v[94:95], v[180:181], v[158:159]
	v_pk_fma_f32 v[178:179], v[92:93], v[180:181], v[178:179]
	v_pk_fma_f32 v[160:161], v[144:145], v[180:181], v[160:161]
	v_lshlrev_b32_e32 v162, 16, v163
	v_and_b32_e32 v163, 0xffff0000, v163
	v_pk_fma_f32 v[164:165], v[126:127], v[162:163], v[164:165]
	v_pk_fma_f32 v[78:79], v[110:111], v[162:163], v[78:79]
	v_pk_fma_f32 v[166:167], v[108:109], v[162:163], v[166:167]
	v_pk_fma_f32 v[80:81], v[106:107], v[162:163], v[80:81]
	v_pk_fma_f32 v[168:169], v[124:125], v[162:163], v[168:169]
	v_pk_fma_f32 v[82:83], v[104:105], v[162:163], v[82:83]
	v_pk_fma_f32 v[170:171], v[102:103], v[162:163], v[170:171]
	v_pk_fma_f32 v[152:153], v[100:101], v[162:163], v[152:153]
	v_pk_fma_f32 v[172:173], v[98:99], v[162:163], v[172:173]
	v_pk_fma_f32 v[154:155], v[90:91], v[162:163], v[154:155]
	v_pk_fma_f32 v[174:175], v[88:89], v[162:163], v[174:175]
	v_pk_fma_f32 v[156:157], v[86:87], v[162:163], v[156:157]
	v_pk_fma_f32 v[176:177], v[96:97], v[162:163], v[176:177]
	v_pk_fma_f32 v[158:159], v[84:85], v[162:163], v[158:159]
	v_pk_fma_f32 v[178:179], v[94:95], v[162:163], v[178:179]
	v_pk_fma_f32 v[160:161], v[92:93], v[162:163], v[160:161]
	s_waitcnt lgkmcnt(13)
; __device__ __forceinline__ float bf_lo(unsigned w) { return __uint_as_float(w << 16); }
; __device__ __forceinline__ float bf_hi(unsigned w) { return __uint_as_float(w & 0xffff0000u); }
; __device__ __forceinline__ void conv_phase(const Frame& F, const bf16* CG, bf16* CAT, const float* dw_w, const float* dw_b, const float* ln_g, const float* ln_b) {
;     ...
;             for (int r = 0; r < 46; ++r) {
;                 const unsigned v = xin[r]; const f32x2 x = (f32x2){bf_lo(v), bf_hi(v)};
; #pragma unroll
;                 for (int tt = 0; tt < 16; ++tt) { const int j = r - tt; if (j >= 0 && j < KC) a[tt] += w[j] * x; }
;             }
	v_lshlrev_b32_e32 v162, 16, v76
	v_and_b32_e32 v163, 0xffff0000, v76
	v_pk_fma_f32 v[164:165], v[112:113], v[162:163], v[164:165]
	v_pk_fma_f32 v[78:79], v[126:127], v[162:163], v[78:79]
	v_pk_fma_f32 v[166:167], v[110:111], v[162:163], v[166:167]
	v_pk_fma_f32 v[80:81], v[108:109], v[162:163], v[80:81]
	v_pk_fma_f32 v[168:169], v[106:107], v[162:163], v[168:169]
	v_pk_fma_f32 v[82:83], v[124:125], v[162:163], v[82:83]
	v_pk_fma_f32 v[170:171], v[104:105], v[162:163], v[170:171]
	v_pk_fma_f32 v[152:153], v[102:103], v[162:163], v[152:153]
	v_pk_fma_f32 v[172:173], v[100:101], v[162:163], v[172:173]
	v_pk_fma_f32 v[154:155], v[98:99], v[162:163], v[154:155]
	v_pk_fma_f32 v[174:175], v[90:91], v[162:163], v[174:175]
	v_pk_fma_f32 v[156:157], v[88:89], v[162:163], v[156:157]
	v_pk_fma_f32 v[176:177], v[86:87], v[162:163], v[176:177]
	v_pk_fma_f32 v[158:159], v[96:97], v[162:163], v[158:159]
	v_pk_fma_f32 v[178:179], v[84:85], v[162:163], v[178:179]
	v_pk_fma_f32 v[160:161], v[94:95], v[162:163], v[160:161]
	v_lshlrev_b32_e32 v76, 16, v77
	v_and_b32_e32 v77, 0xffff0000, v77
	v_pk_fma_f32 v[162:163], v[114:115], v[76:77], v[164:165]
	v_pk_fma_f32 v[78:79], v[112:113], v[76:77], v[78:79]
	v_pk_fma_f32 v[164:165], v[126:127], v[76:77], v[166:167]
	v_pk_fma_f32 v[80:81], v[110:111], v[76:77], v[80:81]
	v_pk_fma_f32 v[166:167], v[108:109], v[76:77], v[168:169]
	v_pk_fma_f32 v[82:83], v[106:107], v[76:77], v[82:83]
	v_pk_fma_f32 v[168:169], v[124:125], v[76:77], v[170:171]
	v_pk_fma_f32 v[152:153], v[104:105], v[76:77], v[152:153]
	v_pk_fma_f32 v[170:171], v[102:103], v[76:77], v[172:173]
	v_pk_fma_f32 v[154:155], v[100:101], v[76:77], v[154:155]
	v_pk_fma_f32 v[172:173], v[98:99], v[76:77], v[174:175]
	v_pk_fma_f32 v[156:157], v[90:91], v[76:77], v[156:157]
	v_pk_fma_f32 v[174:175], v[88:89], v[76:77], v[176:177]
	v_pk_fma_f32 v[158:159], v[86:87], v[76:77], v[158:159]
	v_pk_fma_f32 v[176:177], v[96:97], v[76:77], v[178:179]
	v_pk_fma_f32 v[76:77], v[84:85], v[76:77], v[160:161]
	s_waitcnt lgkmcnt(12)
	v_lshlrev_b32_e32 v160, 16, v74
	v_and_b32_e32 v161, 0xffff0000, v74
	v_pk_fma_f32 v[162:163], v[116:117], v[160:161], v[162:163]
	v_pk_fma_f32 v[78:79], v[114:115], v[160:161], v[78:79]
	v_pk_fma_f32 v[164:165], v[112:113], v[160:161], v[164:165]
	v_pk_fma_f32 v[80:81], v[126:127], v[160:161], v[80:81]
	v_pk_fma_f32 v[166:167], v[110:111], v[160:161], v[166:167]
	v_pk_fma_f32 v[82:83], v[108:109], v[160:161], v[82:83]
	v_pk_fma_f32 v[168:169], v[106:107], v[160:161], v[168:169]
	v_pk_fma_f32 v[152:153], v[124:125], v[160:161], v[152:153]
	v_pk_fma_f32 v[170:171], v[104:105], v[160:161], v[170:171]
	v_pk_fma_f32 v[154:155], v[102:103], v[160:161], v[154:155]
	v_pk_fma_f32 v[172:173], v[100:101], v[160:161], v[172:173]
	v_pk_fma_f32 v[156:157], v[98:99], v[160:161], v[156:157]
	v_pk_fma_f32 v[174:175], v[90:91], v[160:161], v[174:175]
	v_pk_fma_f32 v[158:159], v[88:89], v[160:161], v[158:159]
	v_pk_fma_f32 v[176:177], v[86:87], v[160:161], v[176:177]
	v_pk_fma_f32 v[76:77], v[96:97], v[160:161], v[76:77]
	v_lshlrev_b32_e32 v74, 16, v75
	v_and_b32_e32 v75, 0xffff0000, v75
	v_pk_fma_f32 v[160:161], v[128:129], v[74:75], v[162:163]
	v_pk_fma_f32 v[78:79], v[116:117], v[74:75], v[78:79]
	v_pk_fma_f32 v[162:163], v[114:115], v[74:75], v[164:165]
	v_pk_fma_f32 v[80:81], v[112:113], v[74:75], v[80:81]
	v_pk_fma_f32 v[164:165], v[126:127], v[74:75], v[166:167]
	v_pk_fma_f32 v[82:83], v[110:111], v[74:75], v[82:83]
	v_pk_fma_f32 v[166:167], v[108:109], v[74:75], v[168:169]
	v_pk_fma_f32 v[152:153], v[106:107], v[74:75], v[152:153]
	v_pk_fma_f32 v[168:169], v[124:125], v[74:75], v[170:171]
	v_pk_fma_f32 v[154:155], v[104:105], v[74:75], v[154:155]
	v_pk_fma_f32 v[170:171], v[102:103], v[74:75], v[172:173]
	v_pk_fma_f32 v[156:157], v[100:101], v[74:75], v[156:157]
	v_pk_fma_f32 v[172:173], v[98:99], v[74:75], v[174:175]
	v_pk_fma_f32 v[158:159], v[90:91], v[74:75], v[158:159]
	v_pk_fma_f32 v[174:175], v[88:89], v[74:75], v[176:177]
	v_pk_fma_f32 v[74:75], v[86:87], v[74:75], v[76:77]
	s_waitcnt lgkmcnt(11)
	v_lshlrev_b32_e32 v76, 16, v72
	v_and_b32_e32 v77, 0xffff0000, v72
	v_pk_fma_f32 v[160:161], v[118:119], v[76:77], v[160:161]
	v_pk_fma_f32 v[78:79], v[128:129], v[76:77], v[78:79]
	v_pk_fma_f32 v[162:163], v[116:117], v[76:77], v[162:163]
	v_pk_fma_f32 v[80:81], v[114:115], v[76:77], v[80:81]
	v_pk_fma_f32 v[164:165], v[112:113], v[76:77], v[164:165]
	v_pk_fma_f32 v[82:83], v[126:127], v[76:77], v[82:83]
	v_pk_fma_f32 v[166:167], v[110:111], v[76:77], v[166:167]
	v_pk_fma_f32 v[152:153], v[108:109], v[76:77], v[152:153]
	v_pk_fma_f32 v[168:169], v[106:107], v[76:77], v[168:169]
	v_pk_fma_f32 v[154:155], v[124:125], v[76:77], v[154:155]
	v_pk_fma_f32 v[170:171], v[104:105], v[76:77], v[170:171]
	v_pk_fma_f32 v[156:157], v[102:103], v[76:77], v[156:157]
	v_pk_fma_f32 v[172:173], v[100:101], v[76:77], v[172:173]
	v_pk_fma_f32 v[158:159], v[98:99], v[76:77], v[158:159]
	v_pk_fma_f32 v[174:175], v[90:91], v[76:77], v[174:175]
	v_pk_fma_f32 v[74:75], v[88:89], v[76:77], v[74:75]
	v_lshlrev_b32_e32 v72, 16, v73
	v_and_b32_e32 v73, 0xffff0000, v73
	v_pk_fma_f32 v[76:77], v[120:121], v[72:73], v[160:161]
	v_pk_fma_f32 v[78:79], v[118:119], v[72:73], v[78:79]
	v_pk_fma_f32 v[160:161], v[128:129], v[72:73], v[162:163]
	v_pk_fma_f32 v[80:81], v[116:117], v[72:73], v[80:81]
	v_pk_fma_f32 v[162:163], v[114:115], v[72:73], v[164:165]
	v_pk_fma_f32 v[82:83], v[112:113], v[72:73], v[82:83]
	v_pk_fma_f32 v[164:165], v[126:127], v[72:73], v[166:167]
	v_pk_fma_f32 v[152:153], v[110:111], v[72:73], v[152:153]
	v_pk_fma_f32 v[166:167], v[108:109], v[72:73], v[168:169]
	v_pk_fma_f32 v[154:155], v[106:107], v[72:73], v[154:155]
	v_pk_fma_f32 v[168:169], v[124:125], v[72:73], v[170:171]
	v_pk_fma_f32 v[156:157], v[104:105], v[72:73], v[156:157]
	v_pk_fma_f32 v[170:171], v[102:103], v[72:73], v[172:173]
	v_pk_fma_f32 v[158:159], v[100:101], v[72:73], v[158:159]
	v_pk_fma_f32 v[172:173], v[98:99], v[72:73], v[174:175]
	v_pk_fma_f32 v[72:73], v[90:91], v[72:73], v[74:75]
	s_waitcnt lgkmcnt(10)
; __device__ __forceinline__ float bf_lo(unsigned w) { return __uint_as_float(w << 16); }
; __device__ __forceinline__ float bf_hi(unsigned w) { return __uint_as_float(w & 0xffff0000u); }
; __device__ __forceinline__ void conv_phase(const Frame& F, const bf16* CG, bf16* CAT, const float* dw_w, const float* dw_b, const float* ln_g, const float* ln_b) {
;     ...
;             for (int r = 0; r < 46; ++r) {
;                 const unsigned v = xin[r]; const f32x2 x = (f32x2){bf_lo(v), bf_hi(v)};
; #pragma unroll
;                 for (int tt = 0; tt < 16; ++tt) { const int j = r - tt; if (j >= 0 && j < KC) a[tt] += w[j] * x; }
;             }
	v_lshlrev_b32_e32 v74, 16, v70
	v_and_b32_e32 v75, 0xffff0000, v70
	v_pk_fma_f32 v[76:77], v[122:123], v[74:75], v[76:77]
	v_pk_fma_f32 v[78:79], v[120:121], v[74:75], v[78:79]
	v_pk_fma_f32 v[160:161], v[118:119], v[74:75], v[160:161]
	v_pk_fma_f32 v[80:81], v[128:129], v[74:75], v[80:81]
	v_pk_fma_f32 v[162:163], v[116:117], v[74:75], v[162:163]
	v_pk_fma_f32 v[82:83], v[114:115], v[74:75], v[82:83]
	v_pk_fma_f32 v[164:165], v[112:113], v[74:75], v[164:165]
	v_pk_fma_f32 v[152:153], v[126:127], v[74:75], v[152:153]
	v_pk_fma_f32 v[166:167], v[110:111], v[74:75], v[166:167]
	v_pk_fma_f32 v[154:155], v[108:109], v[74:75], v[154:155]
	v_pk_fma_f32 v[168:169], v[106:107], v[74:75], v[168:169]
	v_pk_fma_f32 v[156:157], v[124:125], v[74:75], v[156:157]
	v_pk_fma_f32 v[170:171], v[104:105], v[74:75], v[170:171]
	v_pk_fma_f32 v[158:159], v[102:103], v[74:75], v[158:159]
	v_pk_fma_f32 v[172:173], v[100:101], v[74:75], v[172:173]
	v_pk_fma_f32 v[72:73], v[98:99], v[74:75], v[72:73]
	v_lshlrev_b32_e32 v70, 16, v71
	v_and_b32_e32 v71, 0xffff0000, v71
	v_pk_fma_f32 v[74:75], v[130:131], v[70:71], v[76:77]
	v_pk_fma_f32 v[76:77], v[122:123], v[70:71], v[78:79]
	v_pk_fma_f32 v[78:79], v[120:121], v[70:71], v[160:161]
	v_pk_fma_f32 v[80:81], v[118:119], v[70:71], v[80:81]
	v_pk_fma_f32 v[160:161], v[128:129], v[70:71], v[162:163]
	v_pk_fma_f32 v[82:83], v[116:117], v[70:71], v[82:83]
	v_pk_fma_f32 v[162:163], v[114:115], v[70:71], v[164:165]
	v_pk_fma_f32 v[152:153], v[112:113], v[70:71], v[152:153]
	v_pk_fma_f32 v[164:165], v[126:127], v[70:71], v[166:167]
	v_pk_fma_f32 v[154:155], v[110:111], v[70:71], v[154:155]
	v_pk_fma_f32 v[166:167], v[108:109], v[70:71], v[168:169]
	v_pk_fma_f32 v[156:157], v[106:107], v[70:71], v[156:157]
	v_pk_fma_f32 v[168:169], v[124:125], v[70:71], v[170:171]
	v_pk_fma_f32 v[158:159], v[104:105], v[70:71], v[158:159]
	v_pk_fma_f32 v[170:171], v[102:103], v[70:71], v[172:173]
	v_pk_fma_f32 v[70:71], v[100:101], v[70:71], v[72:73]
	s_waitcnt lgkmcnt(9)
	v_lshlrev_b32_e32 v72, 16, v68
	v_and_b32_e32 v73, 0xffff0000, v68
	v_pk_fma_f32 v[74:75], v[134:135], v[72:73], v[74:75]
	v_pk_fma_f32 v[76:77], v[130:131], v[72:73], v[76:77]
	v_pk_fma_f32 v[78:79], v[122:123], v[72:73], v[78:79]
	v_pk_fma_f32 v[80:81], v[120:121], v[72:73], v[80:81]
	v_pk_fma_f32 v[160:161], v[118:119], v[72:73], v[160:161]
	v_pk_fma_f32 v[82:83], v[128:129], v[72:73], v[82:83]
	v_pk_fma_f32 v[162:163], v[116:117], v[72:73], v[162:163]
	v_pk_fma_f32 v[152:153], v[114:115], v[72:73], v[152:153]
	v_pk_fma_f32 v[164:165], v[112:113], v[72:73], v[164:165]
	v_pk_fma_f32 v[154:155], v[126:127], v[72:73], v[154:155]
	v_pk_fma_f32 v[166:167], v[110:111], v[72:73], v[166:167]
	v_pk_fma_f32 v[156:157], v[108:109], v[72:73], v[156:157]
	v_pk_fma_f32 v[168:169], v[106:107], v[72:73], v[168:169]
	v_pk_fma_f32 v[158:159], v[124:125], v[72:73], v[158:159]
	v_pk_fma_f32 v[170:171], v[104:105], v[72:73], v[170:171]
	v_pk_fma_f32 v[70:71], v[102:103], v[72:73], v[70:71]
	v_lshlrev_b32_e32 v68, 16, v69
	v_and_b32_e32 v69, 0xffff0000, v69
	v_pk_fma_f32 v[72:73], v[136:137], v[68:69], v[74:75]
	v_pk_fma_f32 v[74:75], v[134:135], v[68:69], v[76:77]
	v_pk_fma_f32 v[76:77], v[130:131], v[68:69], v[78:79]
	v_pk_fma_f32 v[78:79], v[122:123], v[68:69], v[80:81]
	v_pk_fma_f32 v[80:81], v[120:121], v[68:69], v[160:161]
	v_pk_fma_f32 v[82:83], v[118:119], v[68:69], v[82:83]
	v_pk_fma_f32 v[160:161], v[128:129], v[68:69], v[162:163]
	v_pk_fma_f32 v[152:153], v[116:117], v[68:69], v[152:153]
	v_pk_fma_f32 v[162:163], v[114:115], v[68:69], v[164:165]
	v_pk_fma_f32 v[154:155], v[112:113], v[68:69], v[154:155]
	v_pk_fma_f32 v[164:165], v[126:127], v[68:69], v[166:167]
	v_pk_fma_f32 v[156:157], v[110:111], v[68:69], v[156:157]
	v_pk_fma_f32 v[166:167], v[108:109], v[68:69], v[168:169]
	v_pk_fma_f32 v[158:159], v[106:107], v[68:69], v[158:159]
	v_pk_fma_f32 v[168:169], v[124:125], v[68:69], v[170:171]
	v_pk_fma_f32 v[68:69], v[104:105], v[68:69], v[70:71]
	s_waitcnt lgkmcnt(8)
	v_lshlrev_b32_e32 v70, 16, v66
	v_and_b32_e32 v71, 0xffff0000, v66
	v_pk_fma_f32 v[72:73], v[138:139], v[70:71], v[72:73]
	v_pk_fma_f32 v[74:75], v[136:137], v[70:71], v[74:75]
	v_pk_fma_f32 v[76:77], v[134:135], v[70:71], v[76:77]
	v_pk_fma_f32 v[78:79], v[130:131], v[70:71], v[78:79]
	v_pk_fma_f32 v[80:81], v[122:123], v[70:71], v[80:81]
	v_pk_fma_f32 v[82:83], v[120:121], v[70:71], v[82:83]
	v_pk_fma_f32 v[160:161], v[118:119], v[70:71], v[160:161]
	v_pk_fma_f32 v[152:153], v[128:129], v[70:71], v[152:153]
	v_pk_fma_f32 v[162:163], v[116:117], v[70:71], v[162:163]
	v_pk_fma_f32 v[154:155], v[114:115], v[70:71], v[154:155]
	v_pk_fma_f32 v[164:165], v[112:113], v[70:71], v[164:165]
	v_pk_fma_f32 v[156:157], v[126:127], v[70:71], v[156:157]
	v_pk_fma_f32 v[166:167], v[110:111], v[70:71], v[166:167]
	v_pk_fma_f32 v[158:159], v[108:109], v[70:71], v[158:159]
	v_pk_fma_f32 v[168:169], v[106:107], v[70:71], v[168:169]
	v_pk_fma_f32 v[68:69], v[124:125], v[70:71], v[68:69]
	v_lshlrev_b32_e32 v66, 16, v67
	v_and_b32_e32 v67, 0xffff0000, v67
	v_pk_fma_f32 v[70:71], v[132:133], v[66:67], v[72:73]
	v_pk_fma_f32 v[72:73], v[138:139], v[66:67], v[74:75]
	v_pk_fma_f32 v[74:75], v[136:137], v[66:67], v[76:77]
	v_pk_fma_f32 v[76:77], v[134:135], v[66:67], v[78:79]
	v_pk_fma_f32 v[78:79], v[130:131], v[66:67], v[80:81]
	v_pk_fma_f32 v[80:81], v[122:123], v[66:67], v[82:83]
	v_pk_fma_f32 v[82:83], v[120:121], v[66:67], v[160:161]
	v_pk_fma_f32 v[152:153], v[118:119], v[66:67], v[152:153]
	v_pk_fma_f32 v[160:161], v[128:129], v[66:67], v[162:163]
	v_pk_fma_f32 v[154:155], v[116:117], v[66:67], v[154:155]
	v_pk_fma_f32 v[162:163], v[114:115], v[66:67], v[164:165]
	v_pk_fma_f32 v[156:157], v[112:113], v[66:67], v[156:157]
	v_pk_fma_f32 v[164:165], v[126:127], v[66:67], v[166:167]
	v_pk_fma_f32 v[158:159], v[110:111], v[66:67], v[158:159]
	v_pk_fma_f32 v[166:167], v[108:109], v[66:67], v[168:169]
	v_pk_fma_f32 v[66:67], v[106:107], v[66:67], v[68:69]
	s_waitcnt lgkmcnt(7)
; __device__ __forceinline__ float bf_lo(unsigned w) { return __uint_as_float(w << 16); }
; __device__ __forceinline__ float bf_hi(unsigned w) { return __uint_as_float(w & 0xffff0000u); }
; __device__ __forceinline__ void conv_phase(const Frame& F, const bf16* CG, bf16* CAT, const float* dw_w, const float* dw_b, const float* ln_g, const float* ln_b) {
;     ...
;             for (int r = 0; r < 46; ++r) {
;                 const unsigned v = xin[r]; const f32x2 x = (f32x2){bf_lo(v), bf_hi(v)};
; #pragma unroll
;                 for (int tt = 0; tt < 16; ++tt) { const int j = r - tt; if (j >= 0 && j < KC) a[tt] += w[j] * x; }
;             }
	v_lshlrev_b32_e32 v68, 16, v64
	v_and_b32_e32 v69, 0xffff0000, v64
	v_pk_fma_f32 v[72:73], v[132:133], v[68:69], v[72:73]
	v_pk_fma_f32 v[74:75], v[138:139], v[68:69], v[74:75]
	v_pk_fma_f32 v[76:77], v[136:137], v[68:69], v[76:77]
	v_pk_fma_f32 v[78:79], v[134:135], v[68:69], v[78:79]
	v_pk_fma_f32 v[80:81], v[130:131], v[68:69], v[80:81]
	v_pk_fma_f32 v[82:83], v[122:123], v[68:69], v[82:83]
	v_pk_fma_f32 v[152:153], v[120:121], v[68:69], v[152:153]
	v_pk_fma_f32 v[160:161], v[118:119], v[68:69], v[160:161]
	v_pk_fma_f32 v[154:155], v[128:129], v[68:69], v[154:155]
	v_pk_fma_f32 v[162:163], v[116:117], v[68:69], v[162:163]
	v_pk_fma_f32 v[156:157], v[114:115], v[68:69], v[156:157]
	v_pk_fma_f32 v[164:165], v[112:113], v[68:69], v[164:165]
	v_pk_fma_f32 v[158:159], v[126:127], v[68:69], v[158:159]
	v_pk_fma_f32 v[166:167], v[110:111], v[68:69], v[166:167]
	v_pk_fma_f32 v[66:67], v[108:109], v[68:69], v[66:67]
	v_lshlrev_b32_e32 v64, 16, v65
	v_and_b32_e32 v65, 0xffff0000, v65
	v_pk_fma_f32 v[70:71], v[140:141], v[68:69], v[70:71]
	v_pk_fma_f32 v[68:69], v[140:141], v[64:65], v[72:73]
	v_pk_fma_f32 v[72:73], v[132:133], v[64:65], v[74:75]
	v_pk_fma_f32 v[74:75], v[138:139], v[64:65], v[76:77]
	v_pk_fma_f32 v[76:77], v[136:137], v[64:65], v[78:79]
	v_pk_fma_f32 v[78:79], v[134:135], v[64:65], v[80:81]
	v_pk_fma_f32 v[80:81], v[130:131], v[64:65], v[82:83]
	v_pk_fma_f32 v[82:83], v[122:123], v[64:65], v[152:153]
	v_pk_fma_f32 v[152:153], v[120:121], v[64:65], v[160:161]
	v_pk_fma_f32 v[154:155], v[118:119], v[64:65], v[154:155]
	v_pk_fma_f32 v[160:161], v[128:129], v[64:65], v[162:163]
	v_pk_fma_f32 v[156:157], v[116:117], v[64:65], v[156:157]
	v_pk_fma_f32 v[162:163], v[114:115], v[64:65], v[164:165]
	v_pk_fma_f32 v[158:159], v[112:113], v[64:65], v[158:159]
	v_pk_fma_f32 v[164:165], v[126:127], v[64:65], v[166:167]
	v_pk_fma_f32 v[64:65], v[110:111], v[64:65], v[66:67]
	s_waitcnt lgkmcnt(6)
	v_lshlrev_b32_e32 v66, 16, v62
	v_and_b32_e32 v67, 0xffff0000, v62
	v_pk_fma_f32 v[74:75], v[132:133], v[66:67], v[74:75]
	v_pk_fma_f32 v[76:77], v[138:139], v[66:67], v[76:77]
	v_pk_fma_f32 v[78:79], v[136:137], v[66:67], v[78:79]
	v_pk_fma_f32 v[80:81], v[134:135], v[66:67], v[80:81]
	v_pk_fma_f32 v[82:83], v[130:131], v[66:67], v[82:83]
	v_pk_fma_f32 v[152:153], v[122:123], v[66:67], v[152:153]
	v_pk_fma_f32 v[154:155], v[120:121], v[66:67], v[154:155]
	v_pk_fma_f32 v[160:161], v[118:119], v[66:67], v[160:161]
	v_pk_fma_f32 v[156:157], v[128:129], v[66:67], v[156:157]
	v_pk_fma_f32 v[162:163], v[116:117], v[66:67], v[162:163]
	v_pk_fma_f32 v[158:159], v[114:115], v[66:67], v[158:159]
	v_pk_fma_f32 v[164:165], v[112:113], v[66:67], v[164:165]
	v_pk_fma_f32 v[64:65], v[126:127], v[66:67], v[64:65]
	v_lshlrev_b32_e32 v62, 16, v63
	v_and_b32_e32 v63, 0xffff0000, v63
	v_pk_fma_f32 v[72:73], v[140:141], v[66:67], v[72:73]
	v_pk_fma_f32 v[66:67], v[140:141], v[62:63], v[74:75]
	v_pk_fma_f32 v[74:75], v[132:133], v[62:63], v[76:77]
	v_pk_fma_f32 v[76:77], v[138:139], v[62:63], v[78:79]
	v_pk_fma_f32 v[78:79], v[136:137], v[62:63], v[80:81]
	v_pk_fma_f32 v[80:81], v[134:135], v[62:63], v[82:83]
	v_pk_fma_f32 v[82:83], v[130:131], v[62:63], v[152:153]
	v_pk_fma_f32 v[152:153], v[122:123], v[62:63], v[154:155]
	v_pk_fma_f32 v[154:155], v[120:121], v[62:63], v[160:161]
	v_pk_fma_f32 v[156:157], v[118:119], v[62:63], v[156:157]
	v_pk_fma_f32 v[160:161], v[128:129], v[62:63], v[162:163]
	v_pk_fma_f32 v[158:159], v[116:117], v[62:63], v[158:159]
	v_pk_fma_f32 v[162:163], v[114:115], v[62:63], v[164:165]
	v_pk_fma_f32 v[62:63], v[112:113], v[62:63], v[64:65]
	s_waitcnt lgkmcnt(5)
	v_lshlrev_b32_e32 v64, 16, v60
	v_and_b32_e32 v65, 0xffff0000, v60
	v_pk_fma_f32 v[76:77], v[132:133], v[64:65], v[76:77]
	v_pk_fma_f32 v[78:79], v[138:139], v[64:65], v[78:79]
	v_pk_fma_f32 v[80:81], v[136:137], v[64:65], v[80:81]
	v_pk_fma_f32 v[82:83], v[134:135], v[64:65], v[82:83]
	v_pk_fma_f32 v[152:153], v[130:131], v[64:65], v[152:153]
	v_pk_fma_f32 v[154:155], v[122:123], v[64:65], v[154:155]
	v_pk_fma_f32 v[156:157], v[120:121], v[64:65], v[156:157]
	v_pk_fma_f32 v[160:161], v[118:119], v[64:65], v[160:161]
	v_pk_fma_f32 v[158:159], v[128:129], v[64:65], v[158:159]
	v_pk_fma_f32 v[162:163], v[116:117], v[64:65], v[162:163]
	v_pk_fma_f32 v[62:63], v[114:115], v[64:65], v[62:63]
	v_lshlrev_b32_e32 v60, 16, v61
	v_and_b32_e32 v61, 0xffff0000, v61
	v_pk_fma_f32 v[74:75], v[140:141], v[64:65], v[74:75]
	v_pk_fma_f32 v[64:65], v[140:141], v[60:61], v[76:77]
	v_pk_fma_f32 v[76:77], v[132:133], v[60:61], v[78:79]
	v_pk_fma_f32 v[78:79], v[138:139], v[60:61], v[80:81]
	v_pk_fma_f32 v[80:81], v[136:137], v[60:61], v[82:83]
	v_pk_fma_f32 v[82:83], v[134:135], v[60:61], v[152:153]
	v_pk_fma_f32 v[152:153], v[130:131], v[60:61], v[154:155]
	v_pk_fma_f32 v[154:155], v[122:123], v[60:61], v[156:157]
	v_pk_fma_f32 v[156:157], v[120:121], v[60:61], v[160:161]
	v_pk_fma_f32 v[158:159], v[118:119], v[60:61], v[158:159]
	v_pk_fma_f32 v[160:161], v[128:129], v[60:61], v[162:163]
	v_pk_fma_f32 v[60:61], v[116:117], v[60:61], v[62:63]
	s_waitcnt lgkmcnt(4)
; #define LAS __attribute__((address_space(3)))
; __device__ __forceinline__ float bf_lo(unsigned w) { return __uint_as_float(w << 16); }
; __device__ __forceinline__ float bf_hi(unsigned w) { return __uint_as_float(w & 0xffff0000u); }
; __device__ __forceinline__ void conv_phase(const Frame& F, const bf16* CG, bf16* CAT, const float* dw_w, const float* dw_b, const float* ln_g, const float* ln_b) {
;     ...
;             for (int r = 0; r < 46; ++r) {
;                 const unsigned v = xin[r]; const f32x2 x = (f32x2){bf_lo(v), bf_hi(v)};
; #pragma unroll
;                 for (int tt = 0; tt < 16; ++tt) { const int j = r - tt; if (j >= 0 && j < KC) a[tt] += w[j] * x; }
;             }
; #pragma unroll
;             for (int tt = 0; tt < 16; ++tt) *(LAS f32x2*)(yt + (th * 16 + tt) * 512 + 2 * cp) = a[tt];
;         }
;         __syncthreads();
	v_lshlrev_b32_e32 v62, 16, v58
	v_and_b32_e32 v63, 0xffff0000, v58
	v_pk_fma_f32 v[78:79], v[132:133], v[62:63], v[78:79]
	v_pk_fma_f32 v[80:81], v[138:139], v[62:63], v[80:81]
	v_pk_fma_f32 v[82:83], v[136:137], v[62:63], v[82:83]
	v_pk_fma_f32 v[152:153], v[134:135], v[62:63], v[152:153]
	v_pk_fma_f32 v[154:155], v[130:131], v[62:63], v[154:155]
	v_pk_fma_f32 v[156:157], v[122:123], v[62:63], v[156:157]
	v_pk_fma_f32 v[158:159], v[120:121], v[62:63], v[158:159]
	v_pk_fma_f32 v[160:161], v[118:119], v[62:63], v[160:161]
	v_pk_fma_f32 v[60:61], v[128:129], v[62:63], v[60:61]
	v_lshlrev_b32_e32 v58, 16, v59
	v_and_b32_e32 v59, 0xffff0000, v59
	v_pk_fma_f32 v[76:77], v[140:141], v[62:63], v[76:77]
	v_pk_fma_f32 v[62:63], v[140:141], v[58:59], v[78:79]
	v_pk_fma_f32 v[78:79], v[132:133], v[58:59], v[80:81]
	v_pk_fma_f32 v[80:81], v[138:139], v[58:59], v[82:83]
	v_pk_fma_f32 v[82:83], v[136:137], v[58:59], v[152:153]
	v_pk_fma_f32 v[152:153], v[134:135], v[58:59], v[154:155]
	v_pk_fma_f32 v[154:155], v[130:131], v[58:59], v[156:157]
	v_pk_fma_f32 v[156:157], v[122:123], v[58:59], v[158:159]
	v_pk_fma_f32 v[158:159], v[120:121], v[58:59], v[160:161]
	v_pk_fma_f32 v[58:59], v[118:119], v[58:59], v[60:61]
	s_waitcnt lgkmcnt(3)
	v_lshlrev_b32_e32 v60, 16, v56
	v_and_b32_e32 v61, 0xffff0000, v56
	v_pk_fma_f32 v[80:81], v[132:133], v[60:61], v[80:81]
	v_pk_fma_f32 v[82:83], v[138:139], v[60:61], v[82:83]
	v_pk_fma_f32 v[152:153], v[136:137], v[60:61], v[152:153]
	v_pk_fma_f32 v[154:155], v[134:135], v[60:61], v[154:155]
	v_pk_fma_f32 v[156:157], v[130:131], v[60:61], v[156:157]
	v_pk_fma_f32 v[158:159], v[122:123], v[60:61], v[158:159]
	v_pk_fma_f32 v[58:59], v[120:121], v[60:61], v[58:59]
	v_lshlrev_b32_e32 v56, 16, v57
	v_and_b32_e32 v57, 0xffff0000, v57
	v_pk_fma_f32 v[78:79], v[140:141], v[60:61], v[78:79]
	v_pk_fma_f32 v[60:61], v[140:141], v[56:57], v[80:81]
	v_pk_fma_f32 v[80:81], v[132:133], v[56:57], v[82:83]
	v_pk_fma_f32 v[82:83], v[138:139], v[56:57], v[152:153]
	v_pk_fma_f32 v[152:153], v[136:137], v[56:57], v[154:155]
	v_pk_fma_f32 v[154:155], v[134:135], v[56:57], v[156:157]
	v_pk_fma_f32 v[156:157], v[130:131], v[56:57], v[158:159]
	v_pk_fma_f32 v[56:57], v[122:123], v[56:57], v[58:59]
	s_waitcnt lgkmcnt(2)
	v_lshlrev_b32_e32 v58, 16, v54
	v_and_b32_e32 v59, 0xffff0000, v54
	v_pk_fma_f32 v[82:83], v[132:133], v[58:59], v[82:83]
	v_pk_fma_f32 v[152:153], v[138:139], v[58:59], v[152:153]
	v_pk_fma_f32 v[154:155], v[136:137], v[58:59], v[154:155]
	v_pk_fma_f32 v[156:157], v[134:135], v[58:59], v[156:157]
	v_pk_fma_f32 v[56:57], v[130:131], v[58:59], v[56:57]
	v_lshlrev_b32_e32 v54, 16, v55
	v_and_b32_e32 v55, 0xffff0000, v55
	v_pk_fma_f32 v[80:81], v[140:141], v[58:59], v[80:81]
	v_pk_fma_f32 v[58:59], v[140:141], v[54:55], v[82:83]
	v_pk_fma_f32 v[82:83], v[132:133], v[54:55], v[152:153]
	v_pk_fma_f32 v[152:153], v[138:139], v[54:55], v[154:155]
	v_pk_fma_f32 v[154:155], v[136:137], v[54:55], v[156:157]
	v_pk_fma_f32 v[54:55], v[134:135], v[54:55], v[56:57]
	s_waitcnt lgkmcnt(1)
	v_lshlrev_b32_e32 v56, 16, v52
	v_and_b32_e32 v57, 0xffff0000, v52
	v_pk_fma_f32 v[152:153], v[132:133], v[56:57], v[152:153]
	v_pk_fma_f32 v[154:155], v[138:139], v[56:57], v[154:155]
	v_pk_fma_f32 v[54:55], v[136:137], v[56:57], v[54:55]
	v_lshlrev_b32_e32 v52, 16, v53
	v_and_b32_e32 v53, 0xffff0000, v53
	v_pk_fma_f32 v[82:83], v[140:141], v[56:57], v[82:83]
	v_pk_fma_f32 v[56:57], v[140:141], v[52:53], v[152:153]
	v_pk_fma_f32 v[152:153], v[132:133], v[52:53], v[154:155]
	v_pk_fma_f32 v[52:53], v[138:139], v[52:53], v[54:55]
	s_waitcnt lgkmcnt(0)
	v_lshlrev_b32_e32 v54, 16, v2
	v_and_b32_e32 v55, 0xffff0000, v2
	v_pk_fma_f32 v[52:53], v[132:133], v[54:55], v[52:53]
	v_lshlrev_b32_e32 v2, 16, v3
	v_and_b32_e32 v3, 0xffff0000, v3
	v_pk_fma_f32 v[152:153], v[140:141], v[54:55], v[152:153]
	v_pk_fma_f32 v[2:3], v[140:141], v[2:3], v[52:53]
	ds_write2st64_b64 v191, v[70:71], v[68:69] offset1:4
	ds_write2st64_b64 v191, v[72:73], v[66:67] offset0:8 offset1:12
	ds_write2st64_b64 v191, v[74:75], v[64:65] offset0:16 offset1:20
	ds_write2st64_b64 v191, v[76:77], v[62:63] offset0:24 offset1:28
	ds_write2st64_b64 v191, v[78:79], v[60:61] offset0:32 offset1:36
	ds_write2st64_b64 v191, v[80:81], v[58:59] offset0:40 offset1:44
	ds_write2st64_b64 v191, v[82:83], v[56:57] offset0:48 offset1:52
	ds_write2st64_b64 v191, v[152:153], v[2:3] offset0:56 offset1:60
	s_waitcnt lgkmcnt(0)
	s_barrier
; __device__ __forceinline__ unsigned cvt_pk_bf16(float lo, float hi) { unsigned r; asm volatile("v_cvt_pk_bf16_f32 %0, %1, %2" : "=v"(r) : "v"(lo), "v"(hi)); return r; }
; #define LAS __attribute__((address_space(3)))
; __device__ __forceinline__ float sigmoid_f(float x) { return __builtin_amdgcn_rcpf(1.0f + __builtin_amdgcn_exp2f(-1.4426950408889634f * x)); }
; __device__ __forceinline__ void conv_phase(const Frame& F, const bf16* CG, bf16* CAT, const float* dw_w, const float* dw_b, const float* ln_g, const float* ln_b) {
;     ...
;             f32x4 v0[4], v1[4]; float s1[4], s2[4];
; #pragma unroll
;             for (int q = 0; q < 4; ++q) { const int t = wave * 4 + q; v0[q] = *(const LAS f32x4*)(yt + t * 512 + 8 * lane); v1[q] = *(const LAS f32x4*)(yt + t * 512 + 8 * lane + 4); }
; #pragma unroll
;             for (int q = 0; q < 4; ++q) {
;                 s1[q] = (v0[q][0] + v0[q][1]) + (v0[q][2] + v0[q][3]) + (v1[q][0] + v1[q][1]) + (v1[q][2] + v1[q][3]);
;                 s2[q] = (v0[q][0] * v0[q][0] + v0[q][1] * v0[q][1]) + (v0[q][2] * v0[q][2] + v0[q][3] * v0[q][3]) + (v1[q][0] * v1[q][0] + v1[q][1] * v1[q][1]) + (v1[q][2] * v1[q][2] + v1[q][3] * v1[q][3]);
;             }
; #pragma unroll
;             for (int o_ = 1; o_ < 64; o_ <<= 1) {
;                 float t1[4], t2[4];
; #pragma unroll
;                 for (int q = 0; q < 4; ++q) { t1[q] = __shfl_xor(s1[q], o_); t2[q] = __shfl_xor(s2[q], o_); }
; #pragma unroll
;                 for (int q = 0; q < 4; ++q) { s1[q] += t1[q]; s2[q] += t2[q]; }
;             }
; #pragma unroll
;             for (int q = 0; q < 4; ++q) {
;                 const int t = wave * 4 + q;
;                 const float mu = s1[q] * (1.0f / CW), var = fmaxf(s2[q] * (1.0f / CW) - mu * mu, 0.f), rs = __builtin_amdgcn_rsqf(var + EPS);
;                 float o[8];
; #pragma unroll
;                 for (int e = 0; e < 4; ++e) { const float y0 = (v0[q][e] - mu) * rs * lg[0][e] + lb[0][e], y1 = (v1[q][e] - mu) * rs * lg[1][e] + lb[1][e]; o[e] = y0 * sigmoid_f(y0); o[4 + e] = y1 * sigmoid_f(y1); }
;                 v4u wv; wv.x = cvt_pk_bf16(o[0], o[1]); wv.y = cvt_pk_bf16(o[2], o[3]); wv.z = cvt_pk_bf16(o[4], o[5]); wv.w = cvt_pk_bf16(o[6], o[7]);
;                 *(v4u*)(CAT + ((size_t)(b * SEQ + t0 + t) * DM + 8 * lane)) = wv;
;             }
	ds_read_b128 v[80:83], v192 offset:63488
	ds_read_b128 v[76:79], v192 offset:63504
	ds_read_b128 v[72:75], v193 offset:2048
	ds_read_b128 v[68:71], v193 offset:2064
	s_and_b32 s18, s33, 0x1fe0
	s_addk_i32 s46, 0x400
	s_waitcnt lgkmcnt(2)
	v_mul_f32_e32 v58, v76, v76
	v_mul_f32_e32 v2, v80, v80
	v_mul_f32_e32 v52, v81, v81
	v_mul_f32_e32 v54, v82, v82
	v_mul_f32_e32 v56, v83, v83
	v_mov_b32_e32 v3, v80
	v_mov_b32_e32 v53, v81
	v_mov_b32_e32 v55, v82
	v_mov_b32_e32 v57, v83
	v_mul_f32_e32 v60, v77, v77
	v_pk_add_f32 v[2:3], v[2:3], v[52:53]
	v_pk_add_f32 v[52:53], v[54:55], v[56:57]
	v_mov_b32_e32 v59, v76
	v_mov_b32_e32 v61, v77
	v_mul_f32_e32 v62, v78, v78
	v_mul_f32_e32 v64, v79, v79
	v_pk_add_f32 v[2:3], v[2:3], v[52:53]
	v_pk_add_f32 v[52:53], v[58:59], v[60:61]
	v_mov_b32_e32 v63, v78
	v_mov_b32_e32 v65, v79
	v_pk_add_f32 v[2:3], v[2:3], v[52:53]
	v_pk_add_f32 v[52:53], v[62:63], v[64:65]
	s_waitcnt lgkmcnt(1)
	v_mul_f32_e32 v210, v72, v72
	v_pk_add_f32 v[2:3], v[52:53], v[2:3]
	s_nop 1
	v_mov_b32_dpp v153, v3 quad_perm:[1,0,3,2] row_mask:0xf bank_mask:0xf
	v_mov_b32_dpp v152, v2 quad_perm:[1,0,3,2] row_mask:0xf bank_mask:0xf
	v_mul_f32_e32 v214, v73, v73
	v_mul_f32_e32 v216, v74, v74
	v_mul_f32_e32 v218, v75, v75
	v_mov_b32_e32 v211, v72
	s_waitcnt lgkmcnt(0)
	v_pk_add_f32 v[2:3], v[2:3], v[152:153]
	s_nop 1
	v_mov_b32_dpp v153, v3 quad_perm:[2,3,0,1] row_mask:0xf bank_mask:0xf
	v_mov_b32_dpp v152, v2 quad_perm:[2,3,0,1] row_mask:0xf bank_mask:0xf
	v_mov_b32_e32 v215, v73
	v_mov_b32_e32 v217, v74
	v_mov_b32_e32 v219, v75
	v_mul_f32_e32 v220, v68, v68
	s_waitcnt lgkmcnt(0)
	v_pk_add_f32 v[2:3], v[2:3], v[152:153]
	s_nop 1
	v_mov_b32_dpp v153, v3 row_half_mirror row_mask:0xf bank_mask:0xf
	v_mov_b32_dpp v152, v2 row_half_mirror row_mask:0xf bank_mask:0xf
	v_mul_f32_e32 v222, v69, v69
	v_mov_b32_e32 v221, v68
	v_mov_b32_e32 v223, v69
	v_mul_f32_e32 v224, v70, v70
	s_waitcnt lgkmcnt(0)
	v_pk_add_f32 v[2:3], v[2:3], v[152:153]
	s_nop 1
	v_mov_b32_dpp v153, v3 row_mirror row_mask:0xf bank_mask:0xf
	v_mov_b32_dpp v152, v2 row_mirror row_mask:0xf bank_mask:0xf
	v_mul_f32_e32 v226, v71, v71
	v_mov_b32_e32 v225, v70
	v_mov_b32_e32 v227, v71
	ds_read_b128 v[64:67], v193 offset:4096
	ds_read_b128 v[60:63], v193 offset:4112
	ds_read_b128 v[56:59], v193 offset:6144
	ds_read_b128 v[52:55], v193 offset:6160
	s_waitcnt lgkmcnt(4)
	v_pk_add_f32 v[2:3], v[2:3], v[152:153]
	v_mov_b32_e32 v153, v3
	v_mov_b32_e32 v152, v2
	s_nop 1
	v_permlane16_swap_b32_e32 v153, v3
	v_permlane16_swap_b32_e32 v152, v2
	s_waitcnt lgkmcnt(3)
	v_mul_f32_e32 v172, v64, v64
	v_mul_f32_e32 v180, v65, v65
	v_mul_f32_e32 v174, v66, v66
	v_mul_f32_e32 v176, v67, v67
	s_waitcnt lgkmcnt(0)
	v_pk_add_f32 v[2:3], v[2:3], v[152:153]
	v_mov_b32_e32 v159, v3
	v_mov_b32_e32 v158, v2
	s_nop 1
	v_permlane32_swap_b32_e32 v159, v3
	v_permlane32_swap_b32_e32 v158, v2
	v_mov_b32_e32 v173, v64
	v_mov_b32_e32 v181, v65
	v_mov_b32_e32 v175, v66
	v_mov_b32_e32 v177, v67
	s_waitcnt lgkmcnt(0)
	v_pk_add_f32 v[2:3], v[2:3], v[158:159]
	v_mul_f32_e32 v166, v60, v60
	v_pk_mul_f32 v[2:3], v[2:3], s[80:81] op_sel_hi:[1,0]
	v_mul_f32_e32 v178, v61, v61
	v_fma_f32 v1, -v3, v3, v2
	v_max_f32_e32 v1, 0, v1
	v_add_f32_e32 v1, 0x358637bd, v1
	v_rsq_f32_e32 v1, v1
	v_sub_f32_e32 v2, v80, v3
	v_sub_f32_e32 v76, v76, v3
	v_sub_f32_e32 v81, v81, v3
	v_mul_f32_e32 v2, v2, v1
	v_fma_f32 v80, v8, v2, v16
	v_mul_f32_e32 v2, 0xbfb8aa3b, v80
	v_exp_f32_e32 v2, v2
	v_mul_f32_e32 v76, v76, v1
	v_fma_f32 v153, v4, v76, v12
	v_sub_f32_e32 v82, v82, v3
	v_add_f32_e32 v2, 1.0, v2
	v_rcp_f32_e32 v155, v2
	v_mul_f32_e32 v2, 0xbfb8aa3b, v153
	v_exp_f32_e32 v157, v2
	v_mul_f32_e32 v81, v81, v1
	v_mul_f32_e32 v82, v82, v1
	v_fma_f32 v81, v9, v81, v17
	v_fma_f32 v82, v10, v82, v18
	v_mul_f32_e32 v155, v80, v155
	v_add_f32_e32 v80, 1.0, v157
	v_sub_f32_e32 v77, v77, v3
	v_mul_f32_e32 v157, 0xbfb8aa3b, v81
	v_mul_f32_e32 v161, 0xbfb8aa3b, v82
	v_mul_f32_e32 v77, v77, v1
	v_exp_f32_e32 v157, v157
	v_rcp_f32_e32 v80, v80
	v_exp_f32_e32 v161, v161
	v_fma_f32 v77, v5, v77, v13
	v_mul_f32_e32 v159, 0xbfb8aa3b, v77
	v_exp_f32_e32 v159, v159
	v_add_f32_e32 v157, 1.0, v157
	v_mul_f32_e32 v153, v153, v80
	v_add_f32_e32 v80, 1.0, v161
	v_rcp_f32_e32 v157, v157
	v_rcp_f32_e32 v80, v80
	v_add_f32_e32 v159, 1.0, v159
	v_rcp_f32_e32 v159, v159
	v_mul_f32_e32 v157, v81, v157
	v_mul_f32_e32 v161, v82, v80
	v_pk_add_f32 v[80:81], v[210:211], v[214:215]
	v_pk_add_f32 v[210:211], v[216:217], v[218:219]
	v_sub_f32_e32 v78, v78, v3
	v_pk_add_f32 v[80:81], v[80:81], v[210:211]
	v_pk_add_f32 v[210:211], v[220:221], v[222:223]
	v_mul_f32_e32 v78, v78, v1
	v_pk_add_f32 v[80:81], v[80:81], v[210:211]
	v_pk_add_f32 v[210:211], v[224:225], v[226:227]
	v_mul_f32_e32 v77, v77, v159
	v_fma_f32 v159, v6, v78, v14
	v_pk_add_f32 v[80:81], v[210:211], v[80:81]
	v_mul_f32_e32 v78, 0xbfb8aa3b, v159
	s_nop 1
	v_mov_b32_dpp v211, v81 quad_perm:[1,0,3,2] row_mask:0xf bank_mask:0xf
	v_mov_b32_dpp v210, v80 quad_perm:[1,0,3,2] row_mask:0xf bank_mask:0xf
	v_exp_f32_e32 v78, v78
	v_add_u32_e32 v2, s18, v194
	v_mov_b32_e32 v179, v61
	v_mul_f32_e32 v168, v62, v62
	v_add_f32_e32 v78, 1.0, v78
	s_waitcnt lgkmcnt(0)
	v_pk_add_f32 v[80:81], v[80:81], v[210:211]
	v_rcp_f32_e32 v163, v78
	v_sub_f32_e32 v78, v83, v3
	s_nop 1
	v_mov_b32_dpp v83, v81 quad_perm:[2,3,0,1] row_mask:0xf bank_mask:0xf
	v_mov_b32_dpp v82, v80 quad_perm:[2,3,0,1] row_mask:0xf bank_mask:0xf
	v_mul_f32_e32 v78, v78, v1
	v_fma_f32 v165, v11, v78, v19
	v_sub_f32_e32 v3, v79, v3
	v_mul_f32_e32 v1, v3, v1
	s_waitcnt lgkmcnt(0)
; __device__ __forceinline__ unsigned cvt_pk_bf16(float lo, float hi) { unsigned r; asm volatile("v_cvt_pk_bf16_f32 %0, %1, %2" : "=v"(r) : "v"(lo), "v"(hi)); return r; }
; #define LAS __attribute__((address_space(3)))
; __device__ __forceinline__ float sigmoid_f(float x) { return __builtin_amdgcn_rcpf(1.0f + __builtin_amdgcn_exp2f(-1.4426950408889634f * x)); }
; __device__ __forceinline__ void conv_phase(const Frame& F, const bf16* CG, bf16* CAT, const float* dw_w, const float* dw_b, const float* ln_g, const float* ln_b) {
;     ...
;             for (int q = 0; q < 4; ++q) { const int t = wave * 4 + q; v0[q] = *(const LAS f32x4*)(yt + t * 512 + 8 * lane); v1[q] = *(const LAS f32x4*)(yt + t * 512 + 8 * lane + 4); }
; #pragma unroll
;             for (int q = 0; q < 4; ++q) {
;                 s1[q] = (v0[q][0] + v0[q][1]) + (v0[q][2] + v0[q][3]) + (v1[q][0] + v1[q][1]) + (v1[q][2] + v1[q][3]);
;                 s2[q] = (v0[q][0] * v0[q][0] + v0[q][1] * v0[q][1]) + (v0[q][2] * v0[q][2] + v0[q][3] * v0[q][3]) + (v1[q][0] * v1[q][0] + v1[q][1] * v1[q][1]) + (v1[q][2] * v1[q][2] + v1[q][3] * v1[q][3]);
;             }
; #pragma unroll
;             for (int o_ = 1; o_ < 64; o_ <<= 1) {
;                 float t1[4], t2[4];
; #pragma unroll
;                 for (int q = 0; q < 4; ++q) { t1[q] = __shfl_xor(s1[q], o_); t2[q] = __shfl_xor(s2[q], o_); }
; #pragma unroll
;                 for (int q = 0; q < 4; ++q) { s1[q] += t1[q]; s2[q] += t2[q]; }
;             }
; #pragma unroll
;             for (int q = 0; q < 4; ++q) {
;                 const int t = wave * 4 + q;
;                 const float mu = s1[q] * (1.0f / CW), var = fmaxf(s2[q] * (1.0f / CW) - mu * mu, 0.f), rs = __builtin_amdgcn_rsqf(var + EPS);
;                 float o[8];
; #pragma unroll
;                 for (int e = 0; e < 4; ++e) { const float y0 = (v0[q][e] - mu) * rs * lg[0][e] + lb[0][e], y1 = (v1[q][e] - mu) * rs * lg[1][e] + lb[1][e]; o[e] = y0 * sigmoid_f(y0); o[4 + e] = y1 * sigmoid_f(y1); }
;                 v4u wv; wv.x = cvt_pk_bf16(o[0], o[1]); wv.y = cvt_pk_bf16(o[2], o[3]); wv.z = cvt_pk_bf16(o[4], o[5]); wv.w = cvt_pk_bf16(o[6], o[7]);
;                 *(v4u*)(CAT + ((size_t)(b * SEQ + t0 + t) * DM + 8 * lane)) = wv;
;             }
	v_pk_add_f32 v[78:79], v[80:81], v[82:83]
	s_nop 1
	v_mov_b32_dpp v81, v79 row_half_mirror row_mask:0xf bank_mask:0xf
	v_mov_b32_dpp v80, v78 row_half_mirror row_mask:0xf bank_mask:0xf
	v_fma_f32 v1, v7, v1, v15
	v_mul_f32_e32 v82, 0xbfb8aa3b, v1
	v_exp_f32_e32 v82, v82
	v_mul_f32_e32 v3, 0xbfb8aa3b, v165
	s_waitcnt lgkmcnt(0)
	v_pk_add_f32 v[78:79], v[78:79], v[80:81]
	s_nop 1
	v_mov_b32_dpp v81, v79 row_mirror row_mask:0xf bank_mask:0xf
	v_mov_b32_dpp v80, v78 row_mirror row_mask:0xf bank_mask:0xf
	v_add_f32_e32 v82, 1.0, v82
	v_rcp_f32_e32 v167, v82
	v_exp_f32_e32 v3, v3
	v_mul_f32_e32 v159, v159, v163
	s_waitcnt lgkmcnt(0)
	v_pk_add_f32 v[80:81], v[78:79], v[80:81]
	v_mov_b32_e32 v83, v81
	v_mov_b32_e32 v82, v80
	s_nop 1
	v_permlane16_swap_b32_e32 v83, v81
	v_permlane16_swap_b32_e32 v82, v80
	v_add_f32_e32 v3, 1.0, v3
	v_rcp_f32_e32 v3, v3
	v_mul_f32_e32 v1, v1, v167
	v_cvt_pk_bf16_f32 v78, v155, v157
	s_waitcnt lgkmcnt(0)
	v_pk_add_f32 v[82:83], v[80:81], v[82:83]
	v_mov_b32_e32 v211, v83
	v_mov_b32_e32 v210, v82
	s_nop 1
	v_permlane32_swap_b32_e32 v211, v83
	v_permlane32_swap_b32_e32 v210, v82
	v_mul_f32_e32 v3, v165, v3
	v_cvt_pk_bf16_f32 v79, v161, v3
	v_cvt_pk_bf16_f32 v80, v153, v77
	v_cvt_pk_bf16_f32 v81, v159, v1
	s_waitcnt lgkmcnt(0)
	v_pk_add_f32 v[82:83], v[82:83], v[210:211]
	v_ashrrev_i32_e32 v3, 31, v2
	v_pk_mul_f32 v[82:83], v[82:83], s[80:81] op_sel_hi:[1,0]
	v_lshlrev_b64 v[210:211], 11, v[2:3]
	v_fma_f32 v1, -v83, v83, v82
	v_max_f32_e32 v1, 0, v1
	v_add_f32_e32 v1, 0x358637bd, v1
	v_rsq_f32_e32 v1, v1
	v_sub_f32_e32 v3, v72, v83
	v_sub_f32_e32 v68, v68, v83
	v_sub_f32_e32 v73, v73, v83
	v_mul_f32_e32 v3, v3, v1
	v_fma_f32 v3, v8, v3, v16
	v_mul_f32_e32 v72, 0xbfb8aa3b, v3
	v_mul_f32_e32 v68, v68, v1
	v_exp_f32_e32 v72, v72
	v_fma_f32 v68, v4, v68, v12
	v_mul_f32_e32 v73, v73, v1
	v_lshl_add_u64 v[210:211], v[150:151], 0, v[210:211]
	v_mul_f32_e32 v77, 0xbfb8aa3b, v68
	v_fma_f32 v73, v9, v73, v17
	v_exp_f32_e32 v77, v77
	global_store_dwordx4 v[210:211], v[78:81], off
	v_add_f32_e32 v72, 1.0, v72
	v_sub_f32_e32 v69, v69, v83
	v_mul_f32_e32 v78, 0xbfb8aa3b, v73
	v_exp_f32_e32 v78, v78
	v_rcp_f32_e32 v72, v72
	v_mul_f32_e32 v69, v69, v1
	v_fma_f32 v69, v5, v69, v13
	v_add_f32_e32 v77, 1.0, v77
	v_mul_f32_e32 v79, 0xbfb8aa3b, v69
	v_rcp_f32_e32 v77, v77
	v_add_f32_e32 v78, 1.0, v78
	v_exp_f32_e32 v79, v79
	v_rcp_f32_e32 v78, v78
	v_mul_f32_e32 v3, v3, v72
	v_sub_f32_e32 v72, v74, v83
	v_mul_f32_e32 v72, v72, v1
	v_sub_f32_e32 v70, v70, v83
	v_fma_f32 v74, v10, v72, v18
	v_mul_f32_e32 v70, v70, v1
	v_mul_f32_e32 v77, v68, v77
	v_add_f32_e32 v68, 1.0, v79
	v_fma_f32 v70, v6, v70, v14
	v_mul_f32_e32 v72, 0xbfb8aa3b, v74
	v_mul_f32_e32 v78, v73, v78
	v_rcp_f32_e32 v68, v68
	v_exp_f32_e32 v72, v72
	v_mul_f32_e32 v73, 0xbfb8aa3b, v70
	v_exp_f32_e32 v73, v73
	v_mul_f32_e32 v79, v69, v68
	v_add_f32_e32 v68, 1.0, v72
	v_rcp_f32_e32 v80, v68
	v_add_f32_e32 v68, 1.0, v73
	v_rcp_f32_e32 v81, v68
	v_pk_add_f32 v[68:69], v[172:173], v[180:181]
	v_pk_add_f32 v[72:73], v[174:175], v[176:177]
	v_mov_b32_e32 v167, v60
	v_mul_f32_e32 v170, v63, v63
	v_pk_add_f32 v[68:69], v[68:69], v[72:73]
	v_pk_add_f32 v[72:73], v[166:167], v[178:179]
	v_mov_b32_e32 v169, v62
	v_mov_b32_e32 v171, v63
	v_pk_add_f32 v[68:69], v[68:69], v[72:73]
	v_pk_add_f32 v[72:73], v[168:169], v[170:171]
	v_mul_f32_e32 v74, v74, v80
	v_pk_add_f32 v[68:69], v[72:73], v[68:69]
	s_nop 1
	v_mov_b32_dpp v73, v69 quad_perm:[1,0,3,2] row_mask:0xf bank_mask:0xf
	v_mov_b32_dpp v72, v68 quad_perm:[1,0,3,2] row_mask:0xf bank_mask:0xf
	v_mul_f32_e32 v80, v70, v81
	v_sub_f32_e32 v70, v75, v83
	v_mul_f32_e32 v70, v70, v1
	v_fma_f32 v75, v11, v70, v19
	s_waitcnt lgkmcnt(0)
	v_pk_add_f32 v[68:69], v[68:69], v[72:73]
	s_nop 1
	v_mov_b32_dpp v73, v69 quad_perm:[2,3,0,1] row_mask:0xf bank_mask:0xf
	v_mov_b32_dpp v72, v68 quad_perm:[2,3,0,1] row_mask:0xf bank_mask:0xf
	v_sub_f32_e32 v70, v71, v83
	v_mul_f32_e32 v1, v70, v1
	v_fma_f32 v1, v7, v1, v15
	v_mul_f32_e32 v154, v56, v56
	s_waitcnt lgkmcnt(0)
	v_pk_add_f32 v[68:69], v[68:69], v[72:73]
	s_nop 1
	v_mov_b32_dpp v71, v69 row_half_mirror row_mask:0xf bank_mask:0xf
	v_mov_b32_dpp v70, v68 row_half_mirror row_mask:0xf bank_mask:0xf
	v_mul_f32_e32 v72, 0xbfb8aa3b, v75
	v_exp_f32_e32 v72, v72
	v_mul_f32_e32 v73, 0xbfb8aa3b, v1
	v_exp_f32_e32 v73, v73
	s_waitcnt lgkmcnt(0)
	v_pk_add_f32 v[68:69], v[68:69], v[70:71]
	s_nop 1
	v_mov_b32_dpp v71, v69 row_mirror row_mask:0xf bank_mask:0xf
	v_mov_b32_dpp v70, v68 row_mirror row_mask:0xf bank_mask:0xf
	v_add_f32_e32 v72, 1.0, v72
	v_rcp_f32_e32 v81, v72
	v_add_f32_e32 v72, 1.0, v73
	v_rcp_f32_e32 v82, v72
	s_waitcnt lgkmcnt(0)
	v_pk_add_f32 v[70:71], v[68:69], v[70:71]
	v_mov_b32_e32 v73, v71
	v_mov_b32_e32 v72, v70
	s_nop 1
	v_permlane16_swap_b32_e32 v73, v71
	v_permlane16_swap_b32_e32 v72, v70
	v_mul_f32_e32 v69, v75, v81
	v_cvt_pk_bf16_f32 v68, v3, v78
	v_cvt_pk_bf16_f32 v69, v74, v69
	v_mul_f32_e32 v1, v1, v82
	s_waitcnt lgkmcnt(0)
	v_pk_add_f32 v[72:73], v[70:71], v[72:73]
	v_mov_b32_e32 v75, v73
	v_mov_b32_e32 v74, v72
	s_nop 1
	v_permlane32_swap_b32_e32 v75, v73
	v_permlane32_swap_b32_e32 v74, v72
	v_cvt_pk_bf16_f32 v70, v77, v79
	v_cvt_pk_bf16_f32 v71, v80, v1
	v_or_b32_e32 v78, 1, v2
	v_ashrrev_i32_e32 v79, 31, v78
	s_waitcnt lgkmcnt(0)
; __device__ __forceinline__ unsigned cvt_pk_bf16(float lo, float hi) { unsigned r; asm volatile("v_cvt_pk_bf16_f32 %0, %1, %2" : "=v"(r) : "v"(lo), "v"(hi)); return r; }
; __device__ __forceinline__ float sigmoid_f(float x) { return __builtin_amdgcn_rcpf(1.0f + __builtin_amdgcn_exp2f(-1.4426950408889634f * x)); }
; __device__ __forceinline__ void conv_phase(const Frame& F, const bf16* CG, bf16* CAT, const float* dw_w, const float* dw_b, const float* ln_g, const float* ln_b) {
;     ...
;     for (int kk = 0; kk < 8; ++kk) { const int u = ub + 32 * kk;
;     ...
;             for (int q = 0; q < 4; ++q) {
;                 const int t = wave * 4 + q;
;                 const float mu = s1[q] * (1.0f / CW), var = fmaxf(s2[q] * (1.0f / CW) - mu * mu, 0.f), rs = __builtin_amdgcn_rsqf(var + EPS);
;                 float o[8];
; #pragma unroll
;                 for (int e = 0; e < 4; ++e) { const float y0 = (v0[q][e] - mu) * rs * lg[0][e] + lb[0][e], y1 = (v1[q][e] - mu) * rs * lg[1][e] + lb[1][e]; o[e] = y0 * sigmoid_f(y0); o[4 + e] = y1 * sigmoid_f(y1); }
;                 v4u wv; wv.x = cvt_pk_bf16(o[0], o[1]); wv.y = cvt_pk_bf16(o[2], o[3]); wv.z = cvt_pk_bf16(o[4], o[5]); wv.w = cvt_pk_bf16(o[6], o[7]);
;                 *(v4u*)(CAT + ((size_t)(b * SEQ + t0 + t) * DM + 8 * lane)) = wv;
;             }
;         }
	v_pk_add_f32 v[72:73], v[72:73], v[74:75]
	v_lshlrev_b64 v[74:75], 11, v[78:79]
	v_pk_mul_f32 v[72:73], v[72:73], s[80:81] op_sel_hi:[1,0]
	v_lshl_add_u64 v[74:75], v[150:151], 0, v[74:75]
	v_fma_f32 v1, -v73, v73, v72
	v_max_f32_e32 v1, 0, v1
	v_add_f32_e32 v1, 0x358637bd, v1
	v_rsq_f32_e32 v1, v1
	v_sub_f32_e32 v3, v64, v73
	v_sub_f32_e32 v60, v60, v73
	v_sub_f32_e32 v65, v65, v73
	v_mul_f32_e32 v3, v3, v1
	v_fma_f32 v3, v8, v3, v16
	v_mul_f32_e32 v64, 0xbfb8aa3b, v3
	v_mul_f32_e32 v60, v60, v1
	v_exp_f32_e32 v64, v64
	v_fma_f32 v60, v4, v60, v12
	v_mul_f32_e32 v65, v65, v1
	v_mul_f32_e32 v72, 0xbfb8aa3b, v60
	v_fma_f32 v65, v9, v65, v17
	v_exp_f32_e32 v72, v72
	global_store_dwordx4 v[74:75], v[68:71], off
	v_add_f32_e32 v64, 1.0, v64
	v_sub_f32_e32 v61, v61, v73
	v_mul_f32_e32 v69, 0xbfb8aa3b, v65
	v_exp_f32_e32 v69, v69
	v_rcp_f32_e32 v64, v64
	v_mul_f32_e32 v61, v61, v1
	v_fma_f32 v61, v5, v61, v13
	v_add_f32_e32 v68, 1.0, v72
	v_mul_f32_e32 v70, 0xbfb8aa3b, v61
	v_rcp_f32_e32 v68, v68
	v_add_f32_e32 v69, 1.0, v69
	v_exp_f32_e32 v70, v70
	v_rcp_f32_e32 v69, v69
	v_mul_f32_e32 v3, v3, v64
	v_sub_f32_e32 v64, v66, v73
	v_mul_f32_e32 v64, v64, v1
	v_sub_f32_e32 v62, v62, v73
	v_fma_f32 v66, v10, v64, v18
	v_mul_f32_e32 v62, v62, v1
	v_mul_f32_e32 v68, v60, v68
	v_add_f32_e32 v60, 1.0, v70
	v_fma_f32 v62, v6, v62, v14
	v_mul_f32_e32 v64, 0xbfb8aa3b, v66
	v_mul_f32_e32 v69, v65, v69
	v_rcp_f32_e32 v60, v60
	v_exp_f32_e32 v64, v64
	v_mul_f32_e32 v65, 0xbfb8aa3b, v62
	v_exp_f32_e32 v65, v65
	v_mul_f32_e32 v70, v61, v60
	v_add_f32_e32 v60, 1.0, v64
	v_mul_f32_e32 v162, v57, v57
	v_mul_f32_e32 v156, v58, v58
	v_mul_f32_e32 v160, v59, v59
	v_rcp_f32_e32 v71, v60
	v_add_f32_e32 v60, 1.0, v65
	v_mov_b32_e32 v155, v56
	v_mov_b32_e32 v163, v57
	v_mov_b32_e32 v157, v58
	v_mov_b32_e32 v161, v59
	v_mul_f32_e32 v152, v52, v52
	v_mul_f32_e32 v164, v53, v53
	v_rcp_f32_e32 v72, v60
	v_pk_add_f32 v[60:61], v[154:155], v[162:163]
	v_pk_add_f32 v[64:65], v[156:157], v[160:161]
	v_mov_b32_e32 v153, v52
	v_mov_b32_e32 v165, v53
	v_mul_f32_e32 v158, v54, v54
	v_mul_f32_e32 v76, v55, v55
	v_pk_add_f32 v[60:61], v[60:61], v[64:65]
	v_pk_add_f32 v[64:65], v[152:153], v[164:165]
	v_mov_b32_e32 v159, v54
	v_mov_b32_e32 v77, v55
	v_pk_add_f32 v[60:61], v[60:61], v[64:65]
	v_pk_add_f32 v[64:65], v[158:159], v[76:77]
	v_mul_f32_e32 v66, v66, v71
	v_pk_add_f32 v[60:61], v[64:65], v[60:61]
	s_nop 1
	v_mov_b32_dpp v65, v61 quad_perm:[1,0,3,2] row_mask:0xf bank_mask:0xf
	v_mov_b32_dpp v64, v60 quad_perm:[1,0,3,2] row_mask:0xf bank_mask:0xf
	v_mul_f32_e32 v71, v62, v72
	v_sub_f32_e32 v62, v67, v73
	v_mul_f32_e32 v62, v62, v1
	v_fma_f32 v67, v11, v62, v19
	s_waitcnt lgkmcnt(0)
	v_pk_add_f32 v[60:61], v[60:61], v[64:65]
	s_nop 1
	v_mov_b32_dpp v65, v61 quad_perm:[2,3,0,1] row_mask:0xf bank_mask:0xf
	v_mov_b32_dpp v64, v60 quad_perm:[2,3,0,1] row_mask:0xf bank_mask:0xf
	v_sub_f32_e32 v62, v63, v73
	v_mul_f32_e32 v1, v62, v1
	v_fma_f32 v1, v7, v1, v15
	s_cmpk_lg_i32 s46, 0x2000
	s_waitcnt lgkmcnt(0)
	v_pk_add_f32 v[60:61], v[60:61], v[64:65]
	s_nop 1
	v_mov_b32_dpp v63, v61 row_half_mirror row_mask:0xf bank_mask:0xf
	v_mov_b32_dpp v62, v60 row_half_mirror row_mask:0xf bank_mask:0xf
	v_mul_f32_e32 v64, 0xbfb8aa3b, v67
	v_exp_f32_e32 v64, v64
	v_mul_f32_e32 v65, 0xbfb8aa3b, v1
	v_exp_f32_e32 v65, v65
	s_waitcnt lgkmcnt(0)
	v_pk_add_f32 v[60:61], v[60:61], v[62:63]
	s_nop 1
	v_mov_b32_dpp v63, v61 row_mirror row_mask:0xf bank_mask:0xf
	v_mov_b32_dpp v62, v60 row_mirror row_mask:0xf bank_mask:0xf
	v_add_f32_e32 v64, 1.0, v64
	v_rcp_f32_e32 v72, v64
	v_add_f32_e32 v64, 1.0, v65
	v_rcp_f32_e32 v73, v64
	s_waitcnt lgkmcnt(0)
	v_pk_add_f32 v[62:63], v[60:61], v[62:63]
	v_mov_b32_e32 v65, v63
	v_mov_b32_e32 v64, v62
	s_nop 1
	v_permlane16_swap_b32_e32 v65, v63
	v_permlane16_swap_b32_e32 v64, v62
	v_mul_f32_e32 v61, v67, v72
	v_cvt_pk_bf16_f32 v60, v3, v69
	v_cvt_pk_bf16_f32 v61, v66, v61
	v_mul_f32_e32 v1, v1, v73
	s_waitcnt lgkmcnt(0)
	v_pk_add_f32 v[64:65], v[62:63], v[64:65]
	v_mov_b32_e32 v67, v65
	v_mov_b32_e32 v66, v64
	s_nop 1
	v_permlane32_swap_b32_e32 v67, v65
	v_permlane32_swap_b32_e32 v66, v64
	v_cvt_pk_bf16_f32 v62, v68, v70
	v_cvt_pk_bf16_f32 v63, v71, v1
	v_or_b32_e32 v68, 2, v2
	v_ashrrev_i32_e32 v69, 31, v68
	s_waitcnt lgkmcnt(0)
	v_pk_add_f32 v[64:65], v[64:65], v[66:67]
	v_lshlrev_b64 v[66:67], 11, v[68:69]
	v_pk_mul_f32 v[64:65], v[64:65], s[80:81] op_sel_hi:[1,0]
	v_lshl_add_u64 v[66:67], v[150:151], 0, v[66:67]
	v_fma_f32 v1, -v65, v65, v64
	v_max_f32_e32 v1, 0, v1
	v_add_f32_e32 v1, 0x358637bd, v1
	v_rsq_f32_e32 v1, v1
	v_sub_f32_e32 v3, v56, v65
	v_sub_f32_e32 v52, v52, v65
	v_sub_f32_e32 v57, v57, v65
	v_mul_f32_e32 v3, v3, v1
	v_mul_f32_e32 v52, v52, v1
	v_mul_f32_e32 v57, v57, v1
	v_fma_f32 v3, v8, v3, v16
	v_fma_f32 v52, v4, v52, v12
	v_fma_f32 v57, v9, v57, v17
	v_mul_f32_e32 v56, 0xbfb8aa3b, v3
	v_mul_f32_e32 v64, 0xbfb8aa3b, v52
	global_store_dwordx4 v[66:67], v[60:63], off
	v_exp_f32_e32 v56, v56
	v_exp_f32_e32 v64, v64
	v_mul_f32_e32 v61, 0xbfb8aa3b, v57
	v_exp_f32_e32 v61, v61
	v_sub_f32_e32 v53, v53, v65
	v_mul_f32_e32 v53, v53, v1
	v_fma_f32 v53, v5, v53, v13
	v_add_f32_e32 v56, 1.0, v56
	v_add_f32_e32 v60, 1.0, v64
	v_add_f32_e32 v61, 1.0, v61
	v_mul_f32_e32 v62, 0xbfb8aa3b, v53
	v_rcp_f32_e32 v56, v56
	v_rcp_f32_e32 v60, v60
	v_rcp_f32_e32 v61, v61
	v_exp_f32_e32 v62, v62
	v_sub_f32_e32 v58, v58, v65
	v_sub_f32_e32 v54, v54, v65
	v_mul_f32_e32 v58, v58, v1
	v_mul_f32_e32 v54, v54, v1
	v_fma_f32 v58, v10, v58, v18
	v_fma_f32 v54, v6, v54, v14
	v_mul_f32_e32 v3, v3, v56
	v_mul_f32_e32 v56, v52, v60
	v_mul_f32_e32 v52, v57, v61
	v_add_f32_e32 v57, 1.0, v62
	v_mul_f32_e32 v60, 0xbfb8aa3b, v58
	v_mul_f32_e32 v61, 0xbfb8aa3b, v54
	v_rcp_f32_e32 v57, v57
	v_exp_f32_e32 v60, v60
	v_exp_f32_e32 v61, v61
	v_sub_f32_e32 v59, v59, v65
	v_mul_f32_e32 v59, v59, v1
	v_sub_f32_e32 v55, v55, v65
	v_fma_f32 v59, v11, v59, v19
	v_mul_f32_e32 v1, v55, v1
	v_fma_f32 v1, v7, v1, v15
	v_mul_f32_e32 v55, 0xbfb8aa3b, v59
	v_mul_f32_e32 v57, v53, v57
	v_add_f32_e32 v53, 1.0, v60
	v_add_f32_e32 v60, 1.0, v61
	v_exp_f32_e32 v55, v55
	v_mul_f32_e32 v61, 0xbfb8aa3b, v1
	v_exp_f32_e32 v61, v61
	v_rcp_f32_e32 v53, v53
	v_add_f32_e32 v55, 1.0, v55
	v_rcp_f32_e32 v60, v60
	v_rcp_f32_e32 v55, v55
	v_add_f32_e32 v61, 1.0, v61
	v_rcp_f32_e32 v61, v61
	v_or_b32_e32 v2, 3, v2
	v_cvt_pk_bf16_f32 v52, v3, v52
	v_ashrrev_i32_e32 v3, 31, v2
	v_lshlrev_b64 v[2:3], 11, v[2:3]
	v_mul_f32_e32 v53, v58, v53
	v_mul_f32_e32 v58, v54, v60
	v_mul_f32_e32 v54, v59, v55
	v_lshl_add_u64 v[2:3], v[150:151], 0, v[2:3]
	v_mul_f32_e32 v1, v1, v61
	v_cvt_pk_bf16_f32 v53, v53, v54
	v_cvt_pk_bf16_f32 v54, v56, v57
	v_cvt_pk_bf16_f32 v55, v58, v1
	global_store_dwordx4 v[2:3], v[52:55], off
	s_cbranch_scc0 .LBB0_234
